# v56 + P1 rms-stat loads issued before the K-loop (no epilogue wait)
# baseline (speedup 1.0000x reference)
; #define PG8_STAGE(bufoff, gbase, voff) do { _Pragma("unroll") for (int _i = 0; _i < 2; ++_i) \
;         __builtin_amdgcn_global_load_lds((const unsigned*)((const char*)(gbase) + (voff)[_i]), (LAS unsigned*)(lds + (bufoff) + ldsw + _i * 8192), 16, 0, 0); } while (0)
; #define PG8_LDA(dst, b, h) do { _Pragma("unroll") for (int m = 0; m < 4; ++m) _Pragma("unroll") for (int k = 0; k < 2; ++k) dst[m][k] = *(const LAS bf16x8*)(lds + PG8_SA(b, h) + aoff + m * 2048 + k * 1024); } while (0)
; #define PG8_LDB(dst, b, h) do { _Pragma("unroll") for (int n = 0; n < 2; ++n) _Pragma("unroll") for (int k = 0; k < 2; ++k) dst[n][k] = *(const LAS bf16x8*)(lds + PG8_SB(b, h) + boff + n * 2048 + k * 1024); } while (0)
; #define PG8_WAIT_V(n) asm volatile("s_waitcnt vmcnt(" #n ")" ::: "memory")
; #define PG8_WAIT_L(n) asm volatile("s_waitcnt lgkmcnt(" #n ")" ::: "memory")
; #define PG8_BAR __builtin_amdgcn_s_barrier()
; template <int NP> __device__ __forceinline__ void load_rs(const float* ssp, int row0, int fq, float (&rs)[2][4]) {
;     if (NP == 1) {
; #pragma unroll
;         for (int ai = 0; ai < 2; ++ai)
; #pragma unroll
;             for (int m = 0; m < 4; ++m) rs[ai][m] = ssp[row0 + ai * HALF + m * 16];
; template <class Epi>
; __device__ __forceinline__ void gemm_phase(LAS unsigned char* lds, const Gemm g, const StaticOrder& S, const Epi& E) {
;     ...
;         const bool has_next = S.next(ui + 1, nxt);
;         const char* nA = has_next ? (const char*)g.A + (size_t)(nxt.pm >> 5) * aslab + (size_t)(nxt.pm & 31) * tstepA : cA; const char* nB = has_next ? (const char*)g.Bt + (size_t)nxt.pn * tstepB : cB;
;         for (int t = 0; t < nt; t += 2) {
;             const bool last = (t == nt - 2);
;             const char* a1 = cA + (size_t)(t + 1) * kstep;
;             const char* a2 = last ? nA : cA + (size_t)(t + 2) * kstep; const char* b2 = last ? nB : cB + (size_t)(t + 2) * kstep;
;             const char* a3 = a2 + kstep; const char* b3 = b2 + kstep;
;             PG8_LDB(B0, 0, 0); PG8_LDB(B1, 0, 1); PG8_SCHED; PG8_LDA(At, 0, 0); PG8_STAGE(PG8_SA(1, 1), a1 + hstepA, voffA);
;             PG8_WAIT_V(8); PG8_WAIT_L(0); PG8_BAR; PG8_MMA(0, 0, At, B0); PG8_MMA(0, 1, At, B1); PG8_BAR; PG8_SCHED;
;             PG8_LDA(At, 0, 1); PG8_STAGE(PG8_SB(0, 0), b2, voffB); PG8_STAGE(PG8_SB(0, 1), b2 + hstepB, voffB); PG8_STAGE(PG8_SA(0, 0), a2, voffA);
.LBB0_152:
	s_ashr_i32 s20, s56, 5
	s_ashr_i32 s21, s20, 31
	s_lshl_b64 s[20:21], s[20:21], 24
	v_readlane_b32 s22, v235, 38
	v_readlane_b32 s23, v235, 39
	s_add_u32 s19, s22, s20
	s_addc_u32 s21, s23, s21
	s_lshl_b32 s20, s56, 19
	s_and_b32 s20, s20, 0xf80000
	s_add_u32 s20, s19, s20
	s_addc_u32 s21, s21, 0
	s_and_b64 s[22:23], s[0:1], exec
	s_cselect_b32 s58, s21, s25
	s_cselect_b32 s59, s20, s24
	s_ashr_i32 s19, s18, 31
	s_lshl_b64 s[22:23], s[18:19], 19
	s_add_u32 s22, s6, s22
	s_addc_u32 s23, s7, s23
	s_and_b64 s[26:27], s[0:1], exec
	s_cselect_b32 s19, s23, s3
	s_cselect_b32 s60, s22, s2
	s_add_u32 s24, s24, 0x40080
	s_addc_u32 s25, s25, 0
	s_add_u32 s61, s2, 0x100
	s_addc_u32 s62, s3, 0
	s_mov_b32 s63, -2
	s_lshl_b32 s97, s33, 8
	s_add_i32 s97, s97, s48
	v_or_b32_e32 v238, s97, v146
	v_ashrrev_i32_e32 v239, 31, v238
	v_lshl_add_u64 v[238:239], v[238:239], 2, s[72:73]
	global_load_dword v240, v[238:239], off
	global_load_dword v241, v[238:239], off offset:64
	global_load_dword v242, v[238:239], off offset:128
	global_load_dword v243, v[238:239], off offset:192
	global_load_dword v244, v[238:239], off offset:512
	global_load_dword v245, v[238:239], off offset:576
	global_load_dword v246, v[238:239], off offset:640
	global_load_dword v247, v[238:239], off offset:704
	ds_read_b128 v[154:157], v149
	ds_read_b128 v[158:161], v149 offset:1024
	ds_read_b128 v[162:165], v149 offset:2048
	ds_read_b128 v[166:169], v149 offset:3072
	ds_read_b128 v[170:173], v150
	ds_read_b128 v[174:177], v150 offset:1024
	ds_read_b128 v[178:181], v150 offset:2048
	ds_read_b128 v[182:185], v150 offset:3072
	s_add_u32 s2, s24, 0xfffc0080
	s_addc_u32 s3, s25, -1
	s_cmp_eq_u32 s63, 12
	s_cselect_b32 s27, s58, s3
	s_cselect_b32 s26, s59, s2
	s_cselect_b32 s3, s19, s62
	s_cselect_b32 s2, s60, s61
	v_lshl_add_u64 v[144:145], s[24:25], 0, v[136:137]
	s_add_i32 m0, s42, 0xc000
	ds_read_b128 v[190:193], v151
	ds_read_b128 v[198:201], v151 offset:1024
	ds_read_b128 v[202:205], v151 offset:2048
	ds_read_b128 v[206:209], v151 offset:3072
	ds_read_b128 v[210:213], v151 offset:4096
	ds_read_b128 v[214:217], v151 offset:5120
	ds_read_b128 v[218:221], v151 offset:6144
	ds_read_b128 v[222:225], v151 offset:7168
	global_load_lds_dwordx4 v[144:145], off
	v_lshl_add_u64 v[144:145], s[24:25], 0, v[140:141]
	s_add_i32 m0, s42, 0xe000
	s_nop 0
	global_load_lds_dwordx4 v[144:145], off
	s_waitcnt vmcnt(8)
	s_waitcnt lgkmcnt(0)
	s_barrier
	s_waitcnt lgkmcnt(0)
	v_mfma_f32_16x16x32_bf16 v[116:119], v[154:157], v[190:193], 0
	v_mfma_f32_16x16x32_bf16 v[108:111], v[162:165], v[190:193], 0
	v_mfma_f32_16x16x32_bf16 v[104:107], v[154:157], v[202:205], 0
	v_mfma_f32_16x16x32_bf16 v[100:103], v[162:165], v[202:205], 0
	v_mfma_f32_16x16x32_bf16 v[92:95], v[154:157], v[210:213], 0
	v_mfma_f32_16x16x32_bf16 v[84:87], v[162:165], v[210:213], 0
	v_mfma_f32_16x16x32_bf16 v[76:79], v[154:157], v[218:221], 0
	v_mfma_f32_16x16x32_bf16 v[68:71], v[162:165], v[218:221], 0
	v_mfma_f32_16x16x32_bf16 v[116:119], v[158:161], v[198:201], v[116:119]
	v_mfma_f32_16x16x32_bf16 v[108:111], v[166:169], v[198:201], v[108:111]
	v_mfma_f32_16x16x32_bf16 v[104:107], v[158:161], v[206:209], v[104:107]
	v_mfma_f32_16x16x32_bf16 v[100:103], v[166:169], v[206:209], v[100:103]
	v_mfma_f32_16x16x32_bf16 v[92:95], v[158:161], v[214:217], v[92:95]
	v_mfma_f32_16x16x32_bf16 v[84:87], v[166:169], v[214:217], v[84:87]
	v_mfma_f32_16x16x32_bf16 v[76:79], v[158:161], v[222:225], v[76:79]
	v_mfma_f32_16x16x32_bf16 v[68:71], v[166:169], v[222:225], v[68:71]
	v_mfma_f32_16x16x32_bf16 v[124:127], v[170:173], v[190:193], 0
	v_mfma_f32_16x16x32_bf16 v[120:123], v[178:181], v[190:193], 0
	v_mfma_f32_16x16x32_bf16 v[112:115], v[170:173], v[202:205], 0
	v_mfma_f32_16x16x32_bf16 v[96:99], v[178:181], v[202:205], 0
	v_mfma_f32_16x16x32_bf16 v[88:91], v[170:173], v[210:213], 0
	v_mfma_f32_16x16x32_bf16 v[80:83], v[178:181], v[210:213], 0
	v_mfma_f32_16x16x32_bf16 v[72:75], v[170:173], v[218:221], 0
	v_mfma_f32_16x16x32_bf16 v[64:67], v[178:181], v[218:221], 0
	v_mfma_f32_16x16x32_bf16 v[124:127], v[174:177], v[198:201], v[124:127]
	v_mfma_f32_16x16x32_bf16 v[120:123], v[182:185], v[198:201], v[120:123]
	v_mfma_f32_16x16x32_bf16 v[112:115], v[174:177], v[206:209], v[112:115]
	v_mfma_f32_16x16x32_bf16 v[96:99], v[182:185], v[206:209], v[96:99]
	v_mfma_f32_16x16x32_bf16 v[88:91], v[174:177], v[214:217], v[88:91]
	v_mfma_f32_16x16x32_bf16 v[80:83], v[182:185], v[214:217], v[80:83]
	v_mfma_f32_16x16x32_bf16 v[72:75], v[174:177], v[222:225], v[72:75]
	v_mfma_f32_16x16x32_bf16 v[64:67], v[182:185], v[222:225], v[64:67]
	s_barrier
	s_add_i32 s64, s53, s40
	v_lshl_add_u64 v[144:145], s[2:3], 0, v[128:129]
	s_mov_b32 m0, s64
	ds_read_b128 v[190:193], v151 offset:16384
	ds_read_b128 v[198:201], v151 offset:17408
	ds_read_b128 v[202:205], v151 offset:18432
	ds_read_b128 v[206:209], v151 offset:19456
	ds_read_b128 v[210:213], v151 offset:20480
	ds_read_b128 v[214:217], v151 offset:21504
	ds_read_b128 v[218:221], v151 offset:22528
	ds_read_b128 v[222:225], v151 offset:23552
	global_load_lds_dwordx4 v[144:145], off
	s_add_i32 m0, s64, 0x2000
	s_add_u32 s64, s2, 0x40000
	v_lshl_add_u64 v[186:187], s[2:3], 0, v[130:131]
	s_addc_u32 s65, s3, 0
	s_add_i32 s66, s54, s40
	global_load_lds_dwordx4 v[186:187], off
	v_lshl_add_u64 v[194:195], s[64:65], 0, v[128:129]
	s_mov_b32 m0, s66
	v_lshl_add_u64 v[226:227], s[26:27], 0, v[132:133]
	global_load_lds_dwordx4 v[194:195], off
	v_lshl_add_u64 v[194:195], s[64:65], 0, v[130:131]
	s_add_i32 m0, s66, 0x2000
	s_nop 0
	global_load_lds_dwordx4 v[194:195], off
	v_lshl_add_u64 v[194:195], s[26:27], 0, v[134:135]
	s_mov_b32 m0, s42
	s_nop 0
	global_load_lds_dwordx4 v[194:195], off
	s_mov_b32 m0, s43
	s_nop 0
	global_load_lds_dwordx4 v[226:227], off
	s_waitcnt vmcnt(8)
	s_waitcnt lgkmcnt(0)
	s_barrier
; #define PG8_STAGE(bufoff, gbase, voff) do { _Pragma("unroll") for (int _i = 0; _i < 2; ++_i) \
;         __builtin_amdgcn_global_load_lds((const unsigned*)((const char*)(gbase) + (voff)[_i]), (LAS unsigned*)(lds + (bufoff) + ldsw + _i * 8192), 16, 0, 0); } while (0)
; #define PG8_LDA(dst, b, h) do { _Pragma("unroll") for (int m = 0; m < 4; ++m) _Pragma("unroll") for (int k = 0; k < 2; ++k) dst[m][k] = *(const LAS bf16x8*)(lds + PG8_SA(b, h) + aoff + m * 2048 + k * 1024); } while (0)
; #define PG8_LDB(dst, b, h) do { _Pragma("unroll") for (int n = 0; n < 2; ++n) _Pragma("unroll") for (int k = 0; k < 2; ++k) dst[n][k] = *(const LAS bf16x8*)(lds + PG8_SB(b, h) + boff + n * 2048 + k * 1024); } while (0)
; #define PG8_MMA(ai, bj, At, Bt) do { __builtin_amdgcn_s_setprio(1); _Pragma("unroll") for (int m = 0; m < 4; ++m) _Pragma("unroll") for (int n = 0; n < 2; ++n) _Pragma("unroll") for (int k = 0; k < 2; ++k) \
;         acc[ai][bj][m][n] = __builtin_amdgcn_mfma_f32_16x16x32_bf16(Bt[n][k], At[m][k], acc[ai][bj][m][n], 0, 0, 0); __builtin_amdgcn_s_setprio(0); } while (0)
; #define PG8_WAIT_V(n) asm volatile("s_waitcnt vmcnt(" #n ")" ::: "memory")
; #define PG8_WAIT_L(n) asm volatile("s_waitcnt lgkmcnt(" #n ")" ::: "memory")
; #define PG8_BAR __builtin_amdgcn_s_barrier()
; #define PG8_SCHED __builtin_amdgcn_sched_barrier(0)
; template <class Epi>
; __device__ __forceinline__ void gemm_phase(LAS unsigned char* lds, const Gemm g, const StaticOrder& S, const Epi& E) {
;     ...
;             PG8_WAIT_V(8); PG8_WAIT_L(0); PG8_BAR; PG8_MMA(1, 0, At, B0); PG8_MMA(1, 1, At, B1); PG8_BAR; PG8_SCHED;
;             PG8_LDB(B0, 1, 0); PG8_LDB(B1, 1, 1); PG8_SCHED; PG8_LDA(At, 1, 0); PG8_STAGE(PG8_SA(0, 1), a2 + hstepA, voffA);
;             PG8_WAIT_V(8); PG8_WAIT_L(0); PG8_BAR; PG8_MMA(0, 0, At, B0); PG8_MMA(0, 1, At, B1); PG8_BAR; PG8_SCHED;
;             PG8_LDA(At, 1, 1); PG8_STAGE(PG8_SB(1, 0), b3, voffB); PG8_STAGE(PG8_SB(1, 1), b3 + hstepB, voffB); PG8_STAGE(PG8_SA(1, 0), a3, voffA);
	s_waitcnt lgkmcnt(0)
	v_mfma_f32_16x16x32_bf16 v[60:63], v[154:157], v[190:193], 0
	v_mfma_f32_16x16x32_bf16 v[52:55], v[162:165], v[190:193], 0
	v_mfma_f32_16x16x32_bf16 v[44:47], v[154:157], v[202:205], 0
	v_mfma_f32_16x16x32_bf16 v[36:39], v[162:165], v[202:205], 0
	v_mfma_f32_16x16x32_bf16 v[28:31], v[154:157], v[210:213], 0
	v_mfma_f32_16x16x32_bf16 v[20:23], v[162:165], v[210:213], 0
	v_mfma_f32_16x16x32_bf16 v[12:15], v[154:157], v[218:221], 0
	v_mfma_f32_16x16x32_bf16 v[4:7], v[162:165], v[218:221], 0
	v_mfma_f32_16x16x32_bf16 v[60:63], v[158:161], v[198:201], v[60:63]
	v_mfma_f32_16x16x32_bf16 v[52:55], v[166:169], v[198:201], v[52:55]
	v_mfma_f32_16x16x32_bf16 v[44:47], v[158:161], v[206:209], v[44:47]
	v_mfma_f32_16x16x32_bf16 v[36:39], v[166:169], v[206:209], v[36:39]
	v_mfma_f32_16x16x32_bf16 v[28:31], v[158:161], v[214:217], v[28:31]
	v_mfma_f32_16x16x32_bf16 v[20:23], v[166:169], v[214:217], v[20:23]
	v_mfma_f32_16x16x32_bf16 v[12:15], v[158:161], v[222:225], v[12:15]
	v_mfma_f32_16x16x32_bf16 v[4:7], v[166:169], v[222:225], v[4:7]
	v_mfma_f32_16x16x32_bf16 v[56:59], v[170:173], v[190:193], 0
	v_mfma_f32_16x16x32_bf16 v[48:51], v[178:181], v[190:193], 0
	v_mfma_f32_16x16x32_bf16 v[40:43], v[170:173], v[202:205], 0
	v_mfma_f32_16x16x32_bf16 v[32:35], v[178:181], v[202:205], 0
	v_mfma_f32_16x16x32_bf16 v[24:27], v[170:173], v[210:213], 0
	v_mfma_f32_16x16x32_bf16 v[16:19], v[178:181], v[210:213], 0
	v_mfma_f32_16x16x32_bf16 v[8:11], v[170:173], v[218:221], 0
	v_mfma_f32_16x16x32_bf16 v[0:3], v[178:181], v[218:221], 0
	v_mfma_f32_16x16x32_bf16 v[56:59], v[174:177], v[198:201], v[56:59]
	v_mfma_f32_16x16x32_bf16 v[48:51], v[182:185], v[198:201], v[48:51]
	v_mfma_f32_16x16x32_bf16 v[40:43], v[174:177], v[206:209], v[40:43]
	v_mfma_f32_16x16x32_bf16 v[32:35], v[182:185], v[206:209], v[32:35]
	v_mfma_f32_16x16x32_bf16 v[24:27], v[174:177], v[214:217], v[24:27]
	v_mfma_f32_16x16x32_bf16 v[16:19], v[182:185], v[214:217], v[16:19]
	v_mfma_f32_16x16x32_bf16 v[8:11], v[174:177], v[222:225], v[8:11]
	v_mfma_f32_16x16x32_bf16 v[0:3], v[182:185], v[222:225], v[0:3]
	s_barrier
	s_add_i32 s64, 0, 0x18000
	v_add_u32_e32 v138, s64, v147
	s_add_i32 s65, 0, 0x1c000
	ds_read_b128 v[154:157], v138
	ds_read_b128 v[158:161], v138 offset:1024
	ds_read_b128 v[162:165], v138 offset:2048
	ds_read_b128 v[166:169], v138 offset:3072
	v_add_u32_e32 v138, s65, v147
	ds_read_b128 v[170:173], v138
	ds_read_b128 v[174:177], v138 offset:1024
	ds_read_b128 v[178:181], v138 offset:2048
	ds_read_b128 v[182:185], v138 offset:3072
	s_add_u32 s26, s26, 0x40000
	s_addc_u32 s27, s27, 0
	s_mov_b32 m0, s44
	v_lshl_add_u64 v[228:229], s[26:27], 0, v[134:135]
	ds_read_b128 v[190:193], v151 offset:32768
	ds_read_b128 v[198:201], v151 offset:33792
	ds_read_b128 v[202:205], v151 offset:34816
	ds_read_b128 v[206:209], v151 offset:35840
	ds_read_b128 v[210:213], v151 offset:36864
	ds_read_b128 v[214:217], v151 offset:37888
	ds_read_b128 v[218:221], v151 offset:38912
	ds_read_b128 v[222:225], v151 offset:39936
	global_load_lds_dwordx4 v[228:229], off
	v_lshl_add_u64 v[228:229], s[26:27], 0, v[132:133]
	s_mov_b32 m0, s45
	s_nop 0
	global_load_lds_dwordx4 v[228:229], off
	s_waitcnt vmcnt(8)
	s_waitcnt lgkmcnt(0)
	s_barrier
	s_waitcnt lgkmcnt(0)
	v_mfma_f32_16x16x32_bf16 v[116:119], v[154:157], v[190:193], v[116:119]
	v_mfma_f32_16x16x32_bf16 v[108:111], v[162:165], v[190:193], v[108:111]
	v_mfma_f32_16x16x32_bf16 v[104:107], v[154:157], v[202:205], v[104:107]
	v_mfma_f32_16x16x32_bf16 v[100:103], v[162:165], v[202:205], v[100:103]
	v_mfma_f32_16x16x32_bf16 v[92:95], v[154:157], v[210:213], v[92:95]
	v_mfma_f32_16x16x32_bf16 v[84:87], v[162:165], v[210:213], v[84:87]
	v_mfma_f32_16x16x32_bf16 v[76:79], v[154:157], v[218:221], v[76:79]
	v_mfma_f32_16x16x32_bf16 v[68:71], v[162:165], v[218:221], v[68:71]
	v_mfma_f32_16x16x32_bf16 v[116:119], v[158:161], v[198:201], v[116:119]
	v_mfma_f32_16x16x32_bf16 v[108:111], v[166:169], v[198:201], v[108:111]
	v_mfma_f32_16x16x32_bf16 v[104:107], v[158:161], v[206:209], v[104:107]
	v_mfma_f32_16x16x32_bf16 v[100:103], v[166:169], v[206:209], v[100:103]
	v_mfma_f32_16x16x32_bf16 v[92:95], v[158:161], v[214:217], v[92:95]
	v_mfma_f32_16x16x32_bf16 v[84:87], v[166:169], v[214:217], v[84:87]
	v_mfma_f32_16x16x32_bf16 v[76:79], v[158:161], v[222:225], v[76:79]
	v_mfma_f32_16x16x32_bf16 v[68:71], v[166:169], v[222:225], v[68:71]
	v_mfma_f32_16x16x32_bf16 v[124:127], v[170:173], v[190:193], v[124:127]
	v_mfma_f32_16x16x32_bf16 v[120:123], v[178:181], v[190:193], v[120:123]
	v_mfma_f32_16x16x32_bf16 v[112:115], v[170:173], v[202:205], v[112:115]
	v_mfma_f32_16x16x32_bf16 v[96:99], v[178:181], v[202:205], v[96:99]
	v_mfma_f32_16x16x32_bf16 v[88:91], v[170:173], v[210:213], v[88:91]
	v_mfma_f32_16x16x32_bf16 v[80:83], v[178:181], v[210:213], v[80:83]
	v_mfma_f32_16x16x32_bf16 v[72:75], v[170:173], v[218:221], v[72:75]
	v_mfma_f32_16x16x32_bf16 v[64:67], v[178:181], v[218:221], v[64:67]
	v_mfma_f32_16x16x32_bf16 v[124:127], v[174:177], v[198:201], v[124:127]
	v_mfma_f32_16x16x32_bf16 v[120:123], v[182:185], v[198:201], v[120:123]
	v_mfma_f32_16x16x32_bf16 v[112:115], v[174:177], v[206:209], v[112:115]
	v_mfma_f32_16x16x32_bf16 v[96:99], v[182:185], v[206:209], v[96:99]
	v_mfma_f32_16x16x32_bf16 v[88:91], v[174:177], v[214:217], v[88:91]
	v_mfma_f32_16x16x32_bf16 v[80:83], v[182:185], v[214:217], v[80:83]
	v_mfma_f32_16x16x32_bf16 v[72:75], v[174:177], v[222:225], v[72:75]
	v_mfma_f32_16x16x32_bf16 v[64:67], v[182:185], v[222:225], v[64:67]
	s_barrier
; #define PG8_STAGE(bufoff, gbase, voff) do { _Pragma("unroll") for (int _i = 0; _i < 2; ++_i) \
;         __builtin_amdgcn_global_load_lds((const unsigned*)((const char*)(gbase) + (voff)[_i]), (LAS unsigned*)(lds + (bufoff) + ldsw + _i * 8192), 16, 0, 0); } while (0)
; #define PG8_LDA(dst, b, h) do { _Pragma("unroll") for (int m = 0; m < 4; ++m) _Pragma("unroll") for (int k = 0; k < 2; ++k) dst[m][k] = *(const LAS bf16x8*)(lds + PG8_SA(b, h) + aoff + m * 2048 + k * 1024); } while (0)
; #define PG8_MMA(ai, bj, At, Bt) do { __builtin_amdgcn_s_setprio(1); _Pragma("unroll") for (int m = 0; m < 4; ++m) _Pragma("unroll") for (int n = 0; n < 2; ++n) _Pragma("unroll") for (int k = 0; k < 2; ++k) \
;         acc[ai][bj][m][n] = __builtin_amdgcn_mfma_f32_16x16x32_bf16(Bt[n][k], At[m][k], acc[ai][bj][m][n], 0, 0, 0); __builtin_amdgcn_s_setprio(0); } while (0)
; #define PG8_WAIT_V(n) asm volatile("s_waitcnt vmcnt(" #n ")" ::: "memory")
; #define PG8_WAIT_L(n) asm volatile("s_waitcnt lgkmcnt(" #n ")" ::: "memory")
; #define PG8_BAR __builtin_amdgcn_s_barrier()
; #define PG8_SCHED __builtin_amdgcn_sched_barrier(0)
; template <class Epi>
; __device__ __forceinline__ void gemm_phase(LAS unsigned char* lds, const Gemm g, const StaticOrder& S, const Epi& E) {
;     ...
;             PG8_LDA(At, 1, 1); PG8_STAGE(PG8_SB(1, 0), b3, voffB); PG8_STAGE(PG8_SB(1, 1), b3 + hstepB, voffB); PG8_STAGE(PG8_SA(1, 0), a3, voffA);
;             PG8_WAIT_V(8); PG8_WAIT_L(0); PG8_BAR; PG8_MMA(1, 0, At, B0); PG8_MMA(1, 1, At, B1); PG8_BAR; PG8_SCHED;
;         }
	s_add_i32 s26, s64, s40
	v_lshl_add_u64 v[144:145], v[144:145], 0, s[14:15]
	s_mov_b32 m0, s26
	ds_read_b128 v[190:193], v151 offset:49152
	ds_read_b128 v[198:201], v151 offset:50176
	ds_read_b128 v[202:205], v151 offset:51200
	ds_read_b128 v[206:209], v151 offset:52224
	ds_read_b128 v[210:213], v151 offset:53248
	ds_read_b128 v[214:217], v151 offset:54272
	ds_read_b128 v[218:221], v151 offset:55296
	ds_read_b128 v[222:225], v151 offset:56320
	global_load_lds_dwordx4 v[144:145], off
	s_add_i32 m0, s26, 0x2000
	s_add_u32 s2, s2, 0x40080
	v_lshl_add_u64 v[144:145], v[186:187], 0, s[14:15]
	s_addc_u32 s3, s3, 0
	s_add_i32 s26, s65, s40
	global_load_lds_dwordx4 v[144:145], off
	v_lshl_add_u64 v[144:145], s[2:3], 0, v[128:129]
	s_mov_b32 m0, s26
	s_nop 0
	global_load_lds_dwordx4 v[144:145], off
	v_lshl_add_u64 v[144:145], s[2:3], 0, v[130:131]
	s_add_i32 m0, s26, 0x2000
	s_nop 0
	global_load_lds_dwordx4 v[144:145], off
	v_lshl_add_u64 v[144:145], v[194:195], 0, s[14:15]
	s_mov_b32 m0, s49
	s_nop 0
	global_load_lds_dwordx4 v[144:145], off
	v_lshl_add_u64 v[144:145], v[226:227], 0, s[14:15]
	s_mov_b32 m0, s50
	s_nop 0
	global_load_lds_dwordx4 v[144:145], off
	s_waitcnt vmcnt(8)
	s_waitcnt lgkmcnt(0)
	s_barrier
	s_waitcnt lgkmcnt(0)
	v_mfma_f32_16x16x32_bf16 v[60:63], v[154:157], v[190:193], v[60:63]
	v_mfma_f32_16x16x32_bf16 v[52:55], v[162:165], v[190:193], v[52:55]
	v_mfma_f32_16x16x32_bf16 v[44:47], v[154:157], v[202:205], v[44:47]
	v_mfma_f32_16x16x32_bf16 v[36:39], v[162:165], v[202:205], v[36:39]
	v_mfma_f32_16x16x32_bf16 v[28:31], v[154:157], v[210:213], v[28:31]
	v_mfma_f32_16x16x32_bf16 v[20:23], v[162:165], v[210:213], v[20:23]
	v_mfma_f32_16x16x32_bf16 v[12:15], v[154:157], v[218:221], v[12:15]
	v_mfma_f32_16x16x32_bf16 v[4:7], v[162:165], v[218:221], v[4:7]
	v_mfma_f32_16x16x32_bf16 v[60:63], v[158:161], v[198:201], v[60:63]
	v_mfma_f32_16x16x32_bf16 v[52:55], v[166:169], v[198:201], v[52:55]
	v_mfma_f32_16x16x32_bf16 v[44:47], v[158:161], v[206:209], v[44:47]
	v_mfma_f32_16x16x32_bf16 v[36:39], v[166:169], v[206:209], v[36:39]
	v_mfma_f32_16x16x32_bf16 v[28:31], v[158:161], v[214:217], v[28:31]
	v_mfma_f32_16x16x32_bf16 v[20:23], v[166:169], v[214:217], v[20:23]
	v_mfma_f32_16x16x32_bf16 v[12:15], v[158:161], v[222:225], v[12:15]
	v_mfma_f32_16x16x32_bf16 v[4:7], v[166:169], v[222:225], v[4:7]
	v_mfma_f32_16x16x32_bf16 v[56:59], v[170:173], v[190:193], v[56:59]
	v_mfma_f32_16x16x32_bf16 v[48:51], v[178:181], v[190:193], v[48:51]
	v_mfma_f32_16x16x32_bf16 v[40:43], v[170:173], v[202:205], v[40:43]
	v_mfma_f32_16x16x32_bf16 v[32:35], v[178:181], v[202:205], v[32:35]
	v_mfma_f32_16x16x32_bf16 v[24:27], v[170:173], v[210:213], v[24:27]
	v_mfma_f32_16x16x32_bf16 v[16:19], v[178:181], v[210:213], v[16:19]
	v_mfma_f32_16x16x32_bf16 v[8:11], v[170:173], v[218:221], v[8:11]
	v_mfma_f32_16x16x32_bf16 v[0:3], v[178:181], v[218:221], v[0:3]
	v_mfma_f32_16x16x32_bf16 v[56:59], v[174:177], v[198:201], v[56:59]
	v_mfma_f32_16x16x32_bf16 v[48:51], v[182:185], v[198:201], v[48:51]
	v_mfma_f32_16x16x32_bf16 v[40:43], v[174:177], v[206:209], v[40:43]
	v_mfma_f32_16x16x32_bf16 v[32:35], v[182:185], v[206:209], v[32:35]
	v_mfma_f32_16x16x32_bf16 v[24:27], v[174:177], v[214:217], v[24:27]
	v_mfma_f32_16x16x32_bf16 v[16:19], v[182:185], v[214:217], v[16:19]
	v_mfma_f32_16x16x32_bf16 v[8:11], v[174:177], v[222:225], v[8:11]
	v_mfma_f32_16x16x32_bf16 v[0:3], v[182:185], v[222:225], v[0:3]
	s_barrier
	s_add_i32 s63, s63, 2
	s_add_u32 s24, s24, 0x100
	s_addc_u32 s25, s25, 0
	s_add_u32 s61, s61, 0x100
	s_addc_u32 s62, s62, 0
	s_cmp_gt_u32 s63, 13
	s_cbranch_scc0 .LBB0_153

; __device__ __forceinline__ unsigned cvt_pk_bf16(float lo, float hi) { unsigned r; asm volatile("v_cvt_pk_bf16_f32 %0, %1, %2" : "=v"(r) : "v"(lo), "v"(hi)); return r; }
;     __device__ __forceinline__ void operator()(const f32x4 (&acc)[2][2][4][2], const Unit& u, int wr, int wc, int fr, int fq) const {
;         const int row0 = u.pm * BM + wr * 64 + fr, col0 = u.pn * HALF + wc * 32 + 8 * fq;
;         float rs[2][4]; load_rs<NP>(ssp, row0, fq, rs);
; #pragma unroll
;         for (int ai = 0; ai < 2; ++ai)
; #pragma unroll
;             for (int m = 0; m < 4; ++m) {
;                 const int row = row0 + ai * HALF + m * 16; const float r = rs[ai][m];
;                 const float nrl = r * -1.44269504089f, r2 = r * r;
;                 unsigned pk[4];
; #pragma unroll
;                 for (int q = 0; q < 4; ++q) {
;                     const f32x4 ga = acc[ai][0][m][q >> 1], ua = acc[ai][1][m][q >> 1]; const int e0 = 2 * (q & 1);
;                     const f32x2 g = (f32x2){ga[e0], ga[e0 + 1]}, up = (f32x2){ua[e0], ua[e0 + 1]};
;                     const f32x2 t = g * nrl; f32x2 ex; ex.x = __builtin_amdgcn_exp2f(t.x); ex.y = __builtin_amdgcn_exp2f(t.y);
;                     const f32x2 d = ex + 1.0f; f32x2 rc; rc.x = __builtin_amdgcn_rcpf(d.x); rc.y = __builtin_amdgcn_rcpf(d.y);
;                     const f32x2 o = (g * up) * (rc * r2);
;                     pk[q] = cvt_pk_bf16(o.x, o.y);
;                 }
;                 u32x4 w; w.x = pk[0]; w.y = pk[1]; w.z = pk[2]; w.w = pk[3];
;                 *(u32x4*)(U + (size_t)(row >> 13) * U_SLAB + (size_t)(row & (SEQ - 1)) * U_PITCH + col0) = w;
.LBB0_156:
	s_lshl_b32 s2, s33, 8
	s_add_i32 s2, s2, s48
	v_or_b32_e32 v144, s2, v146
	v_ashrrev_i32_e32 v145, 31, v144
	v_lshl_add_u64 v[154:155], v[144:145], 2, s[72:73]
	v_mov_b32_e32 v145, v240
	v_mov_b32_e32 v162, v241
	v_mov_b32_e32 v163, v242
	v_mov_b32_e32 v164, v243
	v_mov_b32_e32 v165, v244
	v_mov_b32_e32 v166, v245
	v_mov_b32_e32 v167, v246
	v_mov_b32_e32 v168, v247
	v_lshl_or_b32 v154, s57, 7, v148
	v_pk_mul_f32 v[156:157], v[108:109], v[120:121]
	s_ashr_i32 s3, s2, 13
	v_pk_mul_f32 v[158:159], v[106:107], v[114:115]
	v_ashrrev_i32_e32 v155, 31, v154
	v_bitop3_b32 v114, s2, v153, v146 bitop3:0xc8
	s_mul_hi_i32 s19, s3, 0x4400000
	s_mul_i32 s3, s3, 0x4400000
	v_readlane_b32 s24, v235, 44
	v_pk_mul_f32 v[160:161], v[104:105], v[112:113]
	v_lshlrev_b64 v[112:113], 1, v[154:155]
	v_mul_u32_u24_e32 v114, 0xb40, v114
	v_readlane_b32 s25, v235, 45
	s_add_u32 s2, s24, s3
	v_lshlrev_b32_e32 v138, 1, v114
	s_addc_u32 s3, s25, s19
	v_lshl_add_u64 v[114:115], s[2:3], 0, v[138:139]
	v_pk_mul_f32 v[124:125], v[116:117], v[124:125]
	v_pk_mul_f32 v[126:127], v[118:119], v[126:127]
	v_pk_mul_f32 v[122:123], v[110:111], v[122:123]
	v_lshl_add_u64 v[114:115], v[114:115], 0, v[112:113]
	v_pk_mul_f32 v[96:97], v[100:101], v[96:97]
	v_pk_mul_f32 v[98:99], v[102:103], v[98:99]
	v_pk_mul_f32 v[88:89], v[92:93], v[88:89]
	v_pk_mul_f32 v[90:91], v[94:95], v[90:91]
	v_pk_mul_f32 v[80:81], v[84:85], v[80:81]
	v_pk_mul_f32 v[82:83], v[86:87], v[82:83]
	v_pk_mul_f32 v[72:73], v[76:77], v[72:73]
	v_pk_mul_f32 v[74:75], v[78:79], v[74:75]
	v_pk_mul_f32 v[64:65], v[68:69], v[64:65]
	v_pk_mul_f32 v[66:67], v[70:71], v[66:67]
	s_mov_b32 s2, 0x43000
	v_pk_mul_f32 v[56:57], v[60:61], v[56:57]
	v_pk_mul_f32 v[58:59], v[62:63], v[58:59]
	v_pk_mul_f32 v[48:49], v[52:53], v[48:49]
	v_pk_mul_f32 v[50:51], v[54:55], v[50:51]
	v_pk_mul_f32 v[40:41], v[44:45], v[40:41]
	v_pk_mul_f32 v[42:43], v[46:47], v[42:43]
	v_pk_mul_f32 v[32:33], v[36:37], v[32:33]
	v_pk_mul_f32 v[34:35], v[38:39], v[34:35]
	v_pk_mul_f32 v[24:25], v[28:29], v[24:25]
	v_pk_mul_f32 v[26:27], v[30:31], v[26:27]
	v_pk_mul_f32 v[16:17], v[20:21], v[16:17]
	v_pk_mul_f32 v[18:19], v[22:23], v[18:19]
	v_pk_mul_f32 v[8:9], v[12:13], v[8:9]
	v_pk_mul_f32 v[10:11], v[14:15], v[10:11]
	v_pk_mul_f32 v[0:1], v[4:5], v[0:1]
	v_pk_mul_f32 v[2:3], v[6:7], v[2:3]
	v_fmamk_f32 v120, v145, 0x3a800000, v152
	v_fmamk_f32 v121, v162, 0x3a800000, v152
	v_fmamk_f32 v138, v163, 0x3a800000, v152
	v_fmamk_f32 v145, v164, 0x3a800000, v152
	v_rsq_f32_e32 v164, v120
	v_fmamk_f32 v154, v165, 0x3a800000, v152
	v_rsq_f32_e32 v165, v121
	v_fmamk_f32 v162, v167, 0x3a800000, v152
	v_rsq_f32_e32 v170, v138
	v_mul_f32_e32 v138, 0xbfb8aa3b, v164
	v_fmamk_f32 v163, v168, 0x3a800000, v152
	v_rsq_f32_e32 v121, v162
	v_mul_f32_e32 v162, 0xbfb8aa3b, v165
	v_pk_mul_f32 v[116:117], v[116:117], v[138:139] op_sel_hi:[1,0]
	v_pk_mul_f32 v[108:109], v[108:109], v[138:139] op_sel_hi:[1,0]
	v_pk_mul_f32 v[118:119], v[118:119], v[138:139] op_sel_hi:[1,0]
	v_pk_mul_f32 v[110:111], v[110:111], v[138:139] op_sel_hi:[1,0]
	v_pk_mul_f32 v[104:105], v[104:105], v[162:163] op_sel_hi:[1,0]
	v_exp_f32_e32 v116, v116
	v_exp_f32_e32 v117, v117
	v_exp_f32_e32 v108, v108
	v_exp_f32_e32 v109, v109
	v_pk_mul_f32 v[106:107], v[106:107], v[162:163] op_sel_hi:[1,0]
	v_exp_f32_e32 v118, v118
	v_exp_f32_e32 v119, v119
	v_exp_f32_e32 v110, v110
	v_exp_f32_e32 v111, v111
	v_exp_f32_e32 v104, v104
	v_exp_f32_e32 v105, v105
	v_exp_f32_e32 v106, v106
	v_exp_f32_e32 v107, v107
	v_fmamk_f32 v155, v166, 0x3a800000, v152
	v_pk_add_f32 v[116:117], v[116:117], 1.0 op_sel_hi:[1,0]
	v_pk_add_f32 v[108:109], v[108:109], 1.0 op_sel_hi:[1,0]
	v_rsq_f32_e32 v155, v155
	v_pk_add_f32 v[118:119], v[118:119], 1.0 op_sel_hi:[1,0]
	v_pk_add_f32 v[110:111], v[110:111], 1.0 op_sel_hi:[1,0]
	v_pk_add_f32 v[104:105], v[104:105], 1.0 op_sel_hi:[1,0]
	v_rcp_f32_e32 v116, v116
	v_rcp_f32_e32 v117, v117
	v_rcp_f32_e32 v108, v108
	v_rcp_f32_e32 v109, v109
	v_pk_add_f32 v[106:107], v[106:107], 1.0 op_sel_hi:[1,0]
	v_rcp_f32_e32 v118, v118
	v_rcp_f32_e32 v119, v119
	v_rcp_f32_e32 v110, v110
	v_rcp_f32_e32 v111, v111
	v_rcp_f32_e32 v104, v104
	v_rcp_f32_e32 v105, v105
	v_rcp_f32_e32 v168, v106
	v_rcp_f32_e32 v169, v107
	v_rsq_f32_e32 v171, v154
	v_mul_f32_e32 v154, v164, v164
	v_mul_f32_e32 v164, v165, v165
	v_pk_mul_f32 v[106:107], v[154:155], v[116:117] op_sel_hi:[0,1]
	v_pk_mul_f32 v[108:109], v[154:155], v[108:109] op_sel_hi:[0,1]
	v_pk_mul_f32 v[116:117], v[154:155], v[118:119] op_sel_hi:[0,1]
	v_pk_mul_f32 v[110:111], v[154:155], v[110:111] op_sel_hi:[0,1]
	v_pk_mul_f32 v[104:105], v[164:165], v[104:105] op_sel_hi:[0,1]
	v_pk_mul_f32 v[106:107], v[124:125], v[106:107]
	v_pk_mul_f32 v[108:109], v[156:157], v[108:109]
	v_pk_mul_f32 v[166:167], v[100:101], v[162:163] op_sel_hi:[1,0]
	v_pk_mul_f32 v[116:117], v[126:127], v[116:117]
	v_pk_mul_f32 v[110:111], v[122:123], v[110:111]
	v_pk_mul_f32 v[118:119], v[160:161], v[104:105]
	v_cvt_pk_bf16_f32 v104, v106, v107
	v_cvt_pk_bf16_f32 v105, v116, v117
	v_cvt_pk_bf16_f32 v106, v108, v109
	v_cvt_pk_bf16_f32 v107, v110, v111
	v_pk_mul_f32 v[108:109], v[164:165], v[168:169] op_sel_hi:[0,1]
	global_store_dwordx4 v[114:115], v[104:107], off
	v_pk_mul_f32 v[108:109], v[158:159], v[108:109]
	v_rsq_f32_e32 v145, v145
	v_exp_f32_e32 v106, v166
	v_exp_f32_e32 v107, v167
	v_cvt_pk_bf16_f32 v104, v118, v119
	v_cvt_pk_bf16_f32 v105, v108, v109
	v_pk_mul_f32 v[108:109], v[102:103], v[162:163] op_sel_hi:[1,0]
	v_pk_add_f32 v[106:107], v[106:107], 1.0 op_sel_hi:[1,0]
	v_exp_f32_e32 v108, v108
	v_exp_f32_e32 v109, v109
	v_rcp_f32_e32 v106, v106
	v_rcp_f32_e32 v107, v107
; __device__ __forceinline__ unsigned cvt_pk_bf16(float lo, float hi) { unsigned r; asm volatile("v_cvt_pk_bf16_f32 %0, %1, %2" : "=v"(r) : "v"(lo), "v"(hi)); return r; }
;     __device__ __forceinline__ void operator()(const f32x4 (&acc)[2][2][4][2], const Unit& u, int wr, int wc, int fr, int fq) const {
;     ...
;         for (int ai = 0; ai < 2; ++ai)
; #pragma unroll
;             for (int m = 0; m < 4; ++m) {
;                 const int row = row0 + ai * HALF + m * 16; const float r = rs[ai][m];
;                 const float nrl = r * -1.44269504089f, r2 = r * r;
;                 unsigned pk[4];
; #pragma unroll
;                 for (int q = 0; q < 4; ++q) {
;                     const f32x4 ga = acc[ai][0][m][q >> 1], ua = acc[ai][1][m][q >> 1]; const int e0 = 2 * (q & 1);
;                     const f32x2 g = (f32x2){ga[e0], ga[e0 + 1]}, up = (f32x2){ua[e0], ua[e0 + 1]};
;                     const f32x2 t = g * nrl; f32x2 ex; ex.x = __builtin_amdgcn_exp2f(t.x); ex.y = __builtin_amdgcn_exp2f(t.y);
;                     const f32x2 d = ex + 1.0f; f32x2 rc; rc.x = __builtin_amdgcn_rcpf(d.x); rc.y = __builtin_amdgcn_rcpf(d.y);
;                     const f32x2 o = (g * up) * (rc * r2);
;                     pk[q] = cvt_pk_bf16(o.x, o.y);
;                 }
;                 u32x4 w; w.x = pk[0]; w.y = pk[1]; w.z = pk[2]; w.w = pk[3];
;                 *(u32x4*)(U + (size_t)(row >> 13) * U_SLAB + (size_t)(row & (SEQ - 1)) * U_PITCH + col0) = w;
	v_rsq_f32_e32 v120, v163
	v_pk_add_f32 v[100:101], v[108:109], 1.0 op_sel_hi:[1,0]
	v_pk_mul_f32 v[102:103], v[164:165], v[106:107] op_sel_hi:[0,1]
	v_rcp_f32_e32 v100, v100
	v_rcp_f32_e32 v101, v101
	v_pk_mul_f32 v[96:97], v[96:97], v[102:103]
	s_nop 0
	v_cvt_pk_bf16_f32 v106, v96, v97
	v_pk_mul_f32 v[96:97], v[164:165], v[100:101] op_sel_hi:[0,1]
	v_pk_mul_f32 v[96:97], v[98:99], v[96:97]
	v_add_co_u32_e32 v100, vcc, s47, v114
	v_cvt_pk_bf16_f32 v107, v96, v97
	v_mul_f32_e32 v96, 0xbfb8aa3b, v170
	v_pk_mul_f32 v[98:99], v[92:93], v[96:97] op_sel_hi:[1,0]
	v_pk_mul_f32 v[92:93], v[94:95], v[96:97] op_sel_hi:[1,0]
	v_exp_f32_e32 v98, v98
	v_exp_f32_e32 v99, v99
	v_exp_f32_e32 v92, v92
	v_exp_f32_e32 v93, v93
	v_addc_co_u32_e32 v101, vcc, 0, v115, vcc
	v_pk_add_f32 v[98:99], v[98:99], 1.0 op_sel_hi:[1,0]
	v_pk_add_f32 v[92:93], v[92:93], 1.0 op_sel_hi:[1,0]
	v_rcp_f32_e32 v98, v98
	v_rcp_f32_e32 v99, v99
	v_rcp_f32_e32 v92, v92
	v_rcp_f32_e32 v93, v93
	global_store_dwordx4 v[100:101], v[104:107], off offset:2048
	v_mul_f32_e32 v100, v170, v170
	v_pk_mul_f32 v[94:95], v[100:101], v[98:99] op_sel_hi:[0,1]
	v_pk_mul_f32 v[88:89], v[88:89], v[94:95]
	v_pk_mul_f32 v[94:95], v[84:85], v[96:97] op_sel_hi:[1,0]
	v_pk_mul_f32 v[92:93], v[100:101], v[92:93] op_sel_hi:[0,1]
	v_exp_f32_e32 v94, v94
	v_exp_f32_e32 v95, v95
	v_pk_mul_f32 v[90:91], v[90:91], v[92:93]
	v_pk_mul_f32 v[92:93], v[86:87], v[96:97] op_sel_hi:[1,0]
	v_cvt_pk_bf16_f32 v88, v88, v89
	v_cvt_pk_bf16_f32 v89, v90, v91
	v_pk_add_f32 v[90:91], v[94:95], 1.0 op_sel_hi:[1,0]
	v_exp_f32_e32 v92, v92
	v_exp_f32_e32 v93, v93
	v_rcp_f32_e32 v90, v90
	v_rcp_f32_e32 v91, v91
	v_pk_add_f32 v[84:85], v[92:93], 1.0 op_sel_hi:[1,0]
	s_nop 0
	v_rcp_f32_e32 v84, v84
	v_rcp_f32_e32 v85, v85
	v_pk_mul_f32 v[86:87], v[100:101], v[90:91] op_sel_hi:[0,1]
	v_pk_mul_f32 v[80:81], v[80:81], v[86:87]
	s_nop 0
	v_cvt_pk_bf16_f32 v90, v80, v81
	v_pk_mul_f32 v[80:81], v[100:101], v[84:85] op_sel_hi:[0,1]
	v_pk_mul_f32 v[80:81], v[82:83], v[80:81]
	v_add_co_u32_e32 v84, vcc, s55, v114
	v_cvt_pk_bf16_f32 v91, v80, v81
	v_mul_f32_e32 v80, 0xbfb8aa3b, v145
	v_pk_mul_f32 v[82:83], v[76:77], v[80:81] op_sel_hi:[1,0]
	v_pk_mul_f32 v[76:77], v[78:79], v[80:81] op_sel_hi:[1,0]
	v_exp_f32_e32 v82, v82
	v_exp_f32_e32 v83, v83
	v_exp_f32_e32 v76, v76
	v_exp_f32_e32 v77, v77
	v_addc_co_u32_e32 v85, vcc, 0, v115, vcc
	v_pk_add_f32 v[82:83], v[82:83], 1.0 op_sel_hi:[1,0]
	v_pk_add_f32 v[76:77], v[76:77], 1.0 op_sel_hi:[1,0]
	v_rcp_f32_e32 v82, v82
	v_rcp_f32_e32 v83, v83
	v_rcp_f32_e32 v76, v76
	v_rcp_f32_e32 v77, v77
	global_store_dwordx4 v[84:85], v[88:91], off
	v_mul_f32_e32 v84, v145, v145
	v_pk_mul_f32 v[78:79], v[84:85], v[82:83] op_sel_hi:[0,1]
	v_pk_mul_f32 v[72:73], v[72:73], v[78:79]
	v_pk_mul_f32 v[78:79], v[68:69], v[80:81] op_sel_hi:[1,0]
	v_pk_mul_f32 v[76:77], v[84:85], v[76:77] op_sel_hi:[0,1]
	v_exp_f32_e32 v78, v78
	v_exp_f32_e32 v79, v79
	v_pk_mul_f32 v[74:75], v[74:75], v[76:77]
	v_pk_mul_f32 v[76:77], v[70:71], v[80:81] op_sel_hi:[1,0]
	v_cvt_pk_bf16_f32 v72, v72, v73
	v_cvt_pk_bf16_f32 v73, v74, v75
	v_pk_add_f32 v[74:75], v[78:79], 1.0 op_sel_hi:[1,0]
	v_exp_f32_e32 v76, v76
	v_exp_f32_e32 v77, v77
	v_rcp_f32_e32 v74, v74
	v_rcp_f32_e32 v75, v75
	v_pk_add_f32 v[68:69], v[76:77], 1.0 op_sel_hi:[1,0]
	s_nop 0
	v_rcp_f32_e32 v68, v68
	v_rcp_f32_e32 v69, v69
	v_pk_mul_f32 v[70:71], v[84:85], v[74:75] op_sel_hi:[0,1]
	v_pk_mul_f32 v[64:65], v[64:65], v[70:71]
	s_nop 0
	v_cvt_pk_bf16_f32 v74, v64, v65
	v_pk_mul_f32 v[64:65], v[84:85], v[68:69] op_sel_hi:[0,1]
	v_pk_mul_f32 v[64:65], v[66:67], v[64:65]
	v_mul_f32_e32 v68, v171, v171
	v_cvt_pk_bf16_f32 v75, v64, v65
	v_add_co_u32_e32 v64, vcc, s2, v114
	s_mov_b32 s2, 0x4400000
	s_nop 0
	v_addc_co_u32_e32 v65, vcc, 0, v115, vcc
	global_store_dwordx4 v[64:65], v[72:75], off offset:2048
	v_add_u32_e32 v65, 0x80, v144
	v_mul_f32_e32 v64, 0xbfb8aa3b, v171
	v_pk_mul_f32 v[66:67], v[60:61], v[64:65] op_sel_hi:[1,0]
	v_ashrrev_i32_e32 v69, 13, v65
	v_exp_f32_e32 v66, v66
	v_exp_f32_e32 v67, v67
	v_and_b32_e32 v65, 0x1fcf, v65
	v_pk_mul_f32 v[60:61], v[62:63], v[64:65] op_sel_hi:[1,0]
	v_pk_add_f32 v[66:67], v[66:67], 1.0 op_sel_hi:[1,0]
	v_exp_f32_e32 v60, v60
	v_exp_f32_e32 v61, v61
	v_rcp_f32_e32 v66, v66
	v_rcp_f32_e32 v67, v67
	v_pk_add_f32 v[60:61], v[60:61], 1.0 op_sel_hi:[1,0]
	s_nop 0
	v_rcp_f32_e32 v60, v60
	v_rcp_f32_e32 v61, v61
	v_pk_mul_f32 v[62:63], v[68:69], v[66:67] op_sel_hi:[0,1]
	v_pk_mul_f32 v[56:57], v[56:57], v[62:63]
	v_pk_mul_f32 v[62:63], v[52:53], v[64:65] op_sel_hi:[1,0]
	v_pk_mul_f32 v[60:61], v[68:69], v[60:61] op_sel_hi:[0,1]
	v_exp_f32_e32 v62, v62
	v_exp_f32_e32 v63, v63
	v_pk_mul_f32 v[58:59], v[58:59], v[60:61]
	v_pk_mul_f32 v[60:61], v[54:55], v[64:65] op_sel_hi:[1,0]
	v_cvt_pk_bf16_f32 v56, v56, v57
	v_cvt_pk_bf16_f32 v57, v58, v59
	v_pk_add_f32 v[58:59], v[62:63], 1.0 op_sel_hi:[1,0]
	v_exp_f32_e32 v60, v60
	v_exp_f32_e32 v61, v61
	v_rcp_f32_e32 v58, v58
	v_rcp_f32_e32 v59, v59
	v_pk_add_f32 v[52:53], v[60:61], 1.0 op_sel_hi:[1,0]
	s_nop 0
	v_rcp_f32_e32 v52, v52
	v_rcp_f32_e32 v53, v53
	v_pk_mul_f32 v[54:55], v[68:69], v[58:59] op_sel_hi:[0,1]
	v_pk_mul_f32 v[48:49], v[48:49], v[54:55]
	v_mul_f32_e32 v54, v155, v155
	v_cvt_pk_bf16_f32 v58, v48, v49
	v_pk_mul_f32 v[48:49], v[68:69], v[52:53] op_sel_hi:[0,1]
; __device__ __forceinline__ unsigned cvt_pk_bf16(float lo, float hi) { unsigned r; asm volatile("v_cvt_pk_bf16_f32 %0, %1, %2" : "=v"(r) : "v"(lo), "v"(hi)); return r; }
; #define PG8_BAR __builtin_amdgcn_s_barrier()
;     __device__ __forceinline__ void operator()(const f32x4 (&acc)[2][2][4][2], const Unit& u, int wr, int wc, int fr, int fq) const {
;     ...
;         for (int ai = 0; ai < 2; ++ai)
; #pragma unroll
;             for (int m = 0; m < 4; ++m) {
;                 const int row = row0 + ai * HALF + m * 16; const float r = rs[ai][m];
;                 const float nrl = r * -1.44269504089f, r2 = r * r;
;                 unsigned pk[4];
; #pragma unroll
;                 for (int q = 0; q < 4; ++q) {
;                     const f32x4 ga = acc[ai][0][m][q >> 1], ua = acc[ai][1][m][q >> 1]; const int e0 = 2 * (q & 1);
;                     const f32x2 g = (f32x2){ga[e0], ga[e0 + 1]}, up = (f32x2){ua[e0], ua[e0 + 1]};
;                     const f32x2 t = g * nrl; f32x2 ex; ex.x = __builtin_amdgcn_exp2f(t.x); ex.y = __builtin_amdgcn_exp2f(t.y);
;                     const f32x2 d = ex + 1.0f; f32x2 rc; rc.x = __builtin_amdgcn_rcpf(d.x); rc.y = __builtin_amdgcn_rcpf(d.y);
;                     const f32x2 o = (g * up) * (rc * r2);
;                     pk[q] = cvt_pk_bf16(o.x, o.y);
;                 }
;                 u32x4 w; w.x = pk[0]; w.y = pk[1]; w.z = pk[2]; w.w = pk[3];
;                 *(u32x4*)(U + (size_t)(row >> 13) * U_SLAB + (size_t)(row & (SEQ - 1)) * U_PITCH + col0) = w;
; template <class Epi>
; __device__ __forceinline__ void gemm_phase(LAS unsigned char* lds, const Gemm g, const StaticOrder& S, const Epi& E) {
;     ...
;         if (!has_next) break;
; #pragma unroll
;         for (int a = 0; a < 2; ++a)
; #pragma unroll
;             for (int b = 0; b < 2; ++b)
; #pragma unroll
;                 for (int m = 0; m < 4; ++m)
; #pragma unroll
;                     for (int n = 0; n < 2; ++n) acc[a][b][m][n] = (f32x4){0.f, 0.f, 0.f, 0.f};
;         cur = nxt; cA = nA; cB = nB; ++ui;
;         if (wr == 1) PG8_BAR;
;     }
	v_pk_mul_f32 v[48:49], v[50:51], v[48:49]
	v_mul_u32_u24_e32 v50, 0xb40, v65
	v_lshlrev_b32_e32 v138, 1, v50
	v_mul_f32_e32 v50, 0xbfb8aa3b, v155
	v_pk_mul_f32 v[52:53], v[44:45], v[50:51] op_sel_hi:[1,0]
	v_pk_mul_f32 v[44:45], v[46:47], v[50:51] op_sel_hi:[1,0]
	v_exp_f32_e32 v52, v52
	v_exp_f32_e32 v53, v53
	v_exp_f32_e32 v44, v44
	v_exp_f32_e32 v45, v45
	v_cvt_pk_bf16_f32 v59, v48, v49
	v_pk_add_f32 v[52:53], v[52:53], 1.0 op_sel_hi:[1,0]
	v_mov_b64_e32 v[48:49], s[24:25]
	v_rcp_f32_e32 v52, v52
	v_rcp_f32_e32 v53, v53
	v_pk_add_f32 v[44:45], v[44:45], 1.0 op_sel_hi:[1,0]
	v_mad_i64_i32 v[48:49], s[2:3], v69, s2, v[48:49]
	v_rcp_f32_e32 v44, v44
	v_rcp_f32_e32 v45, v45
	v_pk_mul_f32 v[46:47], v[54:55], v[52:53] op_sel_hi:[0,1]
	v_pk_mul_f32 v[40:41], v[40:41], v[46:47]
	v_pk_mul_f32 v[46:47], v[36:37], v[50:51] op_sel_hi:[1,0]
	v_pk_mul_f32 v[44:45], v[54:55], v[44:45] op_sel_hi:[0,1]
	v_exp_f32_e32 v46, v46
	v_exp_f32_e32 v47, v47
	v_pk_mul_f32 v[42:43], v[42:43], v[44:45]
	v_pk_mul_f32 v[44:45], v[38:39], v[50:51] op_sel_hi:[1,0]
	v_lshl_add_u64 v[48:49], v[48:49], 0, v[138:139]
	v_exp_f32_e32 v44, v44
	v_exp_f32_e32 v45, v45
	v_lshl_add_u64 v[48:49], v[48:49], 0, v[112:113]
	global_store_dwordx4 v[48:49], v[56:59], off
	v_cvt_pk_bf16_f32 v40, v40, v41
	v_cvt_pk_bf16_f32 v41, v42, v43
	v_pk_add_f32 v[42:43], v[46:47], 1.0 op_sel_hi:[1,0]
	v_pk_add_f32 v[36:37], v[44:45], 1.0 op_sel_hi:[1,0]
	v_rcp_f32_e32 v42, v42
	v_rcp_f32_e32 v43, v43
	v_rcp_f32_e32 v36, v36
	v_rcp_f32_e32 v37, v37
	v_pk_mul_f32 v[38:39], v[54:55], v[42:43] op_sel_hi:[0,1]
	v_pk_mul_f32 v[32:33], v[32:33], v[38:39]
	s_nop 0
	v_cvt_pk_bf16_f32 v42, v32, v33
	v_pk_mul_f32 v[32:33], v[54:55], v[36:37] op_sel_hi:[0,1]
	v_pk_mul_f32 v[32:33], v[34:35], v[32:33]
	v_add_co_u32_e32 v36, vcc, s47, v48
	v_cvt_pk_bf16_f32 v43, v32, v33
	v_mul_f32_e32 v32, 0xbfb8aa3b, v121
	v_pk_mul_f32 v[34:35], v[28:29], v[32:33] op_sel_hi:[1,0]
	v_pk_mul_f32 v[28:29], v[30:31], v[32:33] op_sel_hi:[1,0]
	v_exp_f32_e32 v34, v34
	v_exp_f32_e32 v35, v35
	v_exp_f32_e32 v28, v28
	v_exp_f32_e32 v29, v29
	v_addc_co_u32_e32 v37, vcc, 0, v49, vcc
	v_pk_add_f32 v[34:35], v[34:35], 1.0 op_sel_hi:[1,0]
	v_pk_add_f32 v[28:29], v[28:29], 1.0 op_sel_hi:[1,0]
	v_rcp_f32_e32 v34, v34
	v_rcp_f32_e32 v35, v35
	v_rcp_f32_e32 v28, v28
	v_rcp_f32_e32 v29, v29
	global_store_dwordx4 v[36:37], v[40:43], off offset:2048
	v_mul_f32_e32 v36, v121, v121
	v_pk_mul_f32 v[30:31], v[36:37], v[34:35] op_sel_hi:[0,1]
	v_pk_mul_f32 v[24:25], v[24:25], v[30:31]
	v_pk_mul_f32 v[30:31], v[20:21], v[32:33] op_sel_hi:[1,0]
	v_pk_mul_f32 v[28:29], v[36:37], v[28:29] op_sel_hi:[0,1]
	v_exp_f32_e32 v30, v30
	v_exp_f32_e32 v31, v31
	v_pk_mul_f32 v[26:27], v[26:27], v[28:29]
	v_pk_mul_f32 v[28:29], v[22:23], v[32:33] op_sel_hi:[1,0]
	v_cvt_pk_bf16_f32 v24, v24, v25
	v_cvt_pk_bf16_f32 v25, v26, v27
	v_pk_add_f32 v[26:27], v[30:31], 1.0 op_sel_hi:[1,0]
	v_exp_f32_e32 v28, v28
	v_exp_f32_e32 v29, v29
	v_rcp_f32_e32 v26, v26
	v_rcp_f32_e32 v27, v27
	v_pk_add_f32 v[20:21], v[28:29], 1.0 op_sel_hi:[1,0]
	s_nop 0
	v_rcp_f32_e32 v20, v20
	v_rcp_f32_e32 v21, v21
	v_pk_mul_f32 v[22:23], v[36:37], v[26:27] op_sel_hi:[0,1]
	v_pk_mul_f32 v[16:17], v[16:17], v[22:23]
	s_nop 0
	v_cvt_pk_bf16_f32 v26, v16, v17
	v_pk_mul_f32 v[16:17], v[36:37], v[20:21] op_sel_hi:[0,1]
	v_pk_mul_f32 v[16:17], v[18:19], v[16:17]
	v_add_co_u32_e32 v20, vcc, s55, v48
	v_cvt_pk_bf16_f32 v27, v16, v17
	v_mul_f32_e32 v16, 0xbfb8aa3b, v120
	v_pk_mul_f32 v[18:19], v[12:13], v[16:17] op_sel_hi:[1,0]
	v_pk_mul_f32 v[12:13], v[14:15], v[16:17] op_sel_hi:[1,0]
	v_exp_f32_e32 v18, v18
	v_exp_f32_e32 v19, v19
	v_exp_f32_e32 v12, v12
	v_exp_f32_e32 v13, v13
	v_addc_co_u32_e32 v21, vcc, 0, v49, vcc
	v_pk_add_f32 v[18:19], v[18:19], 1.0 op_sel_hi:[1,0]
	v_pk_add_f32 v[12:13], v[12:13], 1.0 op_sel_hi:[1,0]
	v_rcp_f32_e32 v18, v18
	v_rcp_f32_e32 v19, v19
	v_rcp_f32_e32 v12, v12
	v_rcp_f32_e32 v13, v13
	global_store_dwordx4 v[20:21], v[24:27], off
	v_mul_f32_e32 v20, v120, v120
	v_pk_mul_f32 v[14:15], v[20:21], v[18:19] op_sel_hi:[0,1]
	v_pk_mul_f32 v[8:9], v[8:9], v[14:15]
	v_pk_mul_f32 v[14:15], v[4:5], v[16:17] op_sel_hi:[1,0]
	v_pk_mul_f32 v[12:13], v[20:21], v[12:13] op_sel_hi:[0,1]
	v_exp_f32_e32 v14, v14
	v_exp_f32_e32 v15, v15
	v_pk_mul_f32 v[10:11], v[10:11], v[12:13]
	v_pk_mul_f32 v[12:13], v[6:7], v[16:17] op_sel_hi:[1,0]
	v_cvt_pk_bf16_f32 v8, v8, v9
	v_cvt_pk_bf16_f32 v9, v10, v11
	v_pk_add_f32 v[10:11], v[14:15], 1.0 op_sel_hi:[1,0]
	v_exp_f32_e32 v12, v12
	v_exp_f32_e32 v13, v13
	v_rcp_f32_e32 v10, v10
	v_rcp_f32_e32 v11, v11
	v_pk_add_f32 v[4:5], v[12:13], 1.0 op_sel_hi:[1,0]
	s_nop 0
	v_rcp_f32_e32 v4, v4
	v_rcp_f32_e32 v5, v5
	v_pk_mul_f32 v[6:7], v[20:21], v[10:11] op_sel_hi:[0,1]
	v_pk_mul_f32 v[0:1], v[0:1], v[6:7]
	s_nop 0
	v_cvt_pk_bf16_f32 v10, v0, v1
	v_pk_mul_f32 v[0:1], v[20:21], v[4:5] op_sel_hi:[0,1]
	v_pk_mul_f32 v[0:1], v[2:3], v[0:1]
	s_nop 0
	v_cvt_pk_bf16_f32 v11, v0, v1
	v_add_co_u32_e32 v0, vcc, 0x43000, v48
	s_nop 1
	v_addc_co_u32_e32 v1, vcc, 0, v49, vcc
	s_andn2_b64 vcc, exec, s[0:1]
	s_mov_b64 s[0:1], -1
	global_store_dwordx4 v[0:1], v[8:11], off offset:2048
	s_cbranch_vccnz .LBB0_149
	s_andn2_b64 vcc, exec, s[8:9]
	s_cbranch_vccnz .LBB0_148
	s_barrier
	s_branch .LBB0_148

; #define LAS __attribute__((address_space(3)))
; __global__ void __launch_bounds__(512, 2) mk_fwd(Args a) {
;     extern __shared__ __attribute__((aligned(16))) unsigned char lds_raw[];
;     LAS unsigned char* lds = (LAS unsigned char*)lds_raw;
;     cg::grid_group grid = cg::this_grid();
;     const int tid = threadIdx.x, lane = tid & 63, wave = __builtin_amdgcn_readfirstlane(tid >> 6);
;     const int G = gridDim.x, bx = blockIdx.x;
	.amdhsa_kernel _Z6mk_fwd4Args
		.amdhsa_group_segment_fixed_size 0
		.amdhsa_private_segment_fixed_size 0
		.amdhsa_kernarg_size 408
		.amdhsa_user_sgpr_count 2
		.amdhsa_user_sgpr_dispatch_ptr 0
		.amdhsa_user_sgpr_queue_ptr 0
		.amdhsa_user_sgpr_kernarg_segment_ptr 1
		.amdhsa_user_sgpr_dispatch_id 0
		.amdhsa_user_sgpr_kernarg_preload_length 0
		.amdhsa_user_sgpr_kernarg_preload_offset 0
		.amdhsa_user_sgpr_private_segment_size 0
		.amdhsa_uses_dynamic_stack 0
		.amdhsa_enable_private_segment 0
		.amdhsa_system_sgpr_workgroup_id_x 1
		.amdhsa_system_sgpr_workgroup_id_y 0
		.amdhsa_system_sgpr_workgroup_id_z 0
		.amdhsa_system_sgpr_workgroup_info 0
		.amdhsa_system_vgpr_workitem_id 2
		.amdhsa_next_free_vgpr 248
		.amdhsa_next_free_sgpr 102
		.amdhsa_accum_offset 248
		.amdhsa_reserve_vcc 1
		.amdhsa_float_round_mode_32 0
		.amdhsa_float_round_mode_16_64 0
		.amdhsa_float_denorm_mode_32 3
		.amdhsa_float_denorm_mode_16_64 3
		.amdhsa_dx10_clamp 1
		.amdhsa_ieee_mode 1
		.amdhsa_fp16_overflow 0
		.amdhsa_tg_split 0
		.amdhsa_exception_fp_ieee_invalid_op 0
		.amdhsa_exception_fp_denorm_src 0
		.amdhsa_exception_fp_ieee_div_zero 0
		.amdhsa_exception_fp_ieee_overflow 0
		.amdhsa_exception_fp_ieee_underflow 0
		.amdhsa_exception_fp_ieee_inexact 0
		.amdhsa_exception_int_div_zero 0
	.end_amdhsa_kernel

; #define LAS __attribute__((address_space(3)))
; __global__ void __launch_bounds__(512, 2) mk_fwd(Args a) {
;     extern __shared__ __attribute__((aligned(16))) unsigned char lds_raw[];
;     LAS unsigned char* lds = (LAS unsigned char*)lds_raw;
;     cg::grid_group grid = cg::this_grid();
;     const int tid = threadIdx.x, lane = tid & 63, wave = __builtin_amdgcn_readfirstlane(tid >> 6);
;     const int G = gridDim.x, bx = blockIdx.x;
amdhsa.kernels:
  - .agpr_count:     0
    .args:
      - .offset:         0
        .size:           152
        .value_kind:     by_value
      - .offset:         152
        .size:           4
        .value_kind:     hidden_block_count_x
      - .offset:         156
        .size:           4
        .value_kind:     hidden_block_count_y
      - .offset:         160
        .size:           4
        .value_kind:     hidden_block_count_z
      - .offset:         164
        .size:           2
        .value_kind:     hidden_group_size_x
      - .offset:         166
        .size:           2
        .value_kind:     hidden_group_size_y
      - .offset:         168
        .size:           2
        .value_kind:     hidden_group_size_z
      - .offset:         170
        .size:           2
        .value_kind:     hidden_remainder_x
      - .offset:         172
        .size:           2
        .value_kind:     hidden_remainder_y
      - .offset:         174
        .size:           2
        .value_kind:     hidden_remainder_z
      - .offset:         192
        .size:           8
        .value_kind:     hidden_global_offset_x
      - .offset:         200
        .size:           8
        .value_kind:     hidden_global_offset_y
      - .offset:         208
        .size:           8
        .value_kind:     hidden_global_offset_z
      - .offset:         216
        .size:           2
        .value_kind:     hidden_grid_dims
      - .offset:         240
        .size:           8
        .value_kind:     hidden_multigrid_sync_arg
      - .offset:         272
        .size:           4
        .value_kind:     hidden_dynamic_lds_size
    .group_segment_fixed_size: 0
    .kernarg_segment_align: 8
    .kernarg_segment_size: 408
    .language:       OpenCL C
    .language_version:
      - 2
      - 0
    .max_flat_workgroup_size: 512
    .name:           _Z6mk_fwd4Args
    .private_segment_fixed_size: 0
    .sgpr_count:     108
    .sgpr_spill_count: 94
    .symbol:         _Z6mk_fwd4Args.kd
    .uniform_work_group_size: 1
    .uses_dynamic_stack: false
    .vgpr_count:     248
    .vgpr_spill_count: 0
    .wavefront_size: 64
